# attention B far loop: per-head far bias folded into the exp2 argument (28 adds per tile dropped, max/exp reference shifted by the bias)
# baseline (speedup 1.0000x reference)
; #define LAS __attribute__((address_space(3)))
; template <int DQK, bool MB> ...
;     ...
;         if (act) {
;             bf16x8 kfa[KK], kfb[KK];
; #pragma unroll
;             for (int kk = 0; kk < KK; ++kk) kfa[kk] = *(const LAS bf16x8*)(kb + kk * 1024 + koff);
; #pragma unroll
;             for (int ks = 0; ks < 4; ++ks) {
;                 if (ks < 3) {
; #pragma unroll
;                     for (int kk = 0; kk < KK; ++kk) { const bf16x8 t = *(const LAS bf16x8*)(kb + ((ks + 1) * KK + kk) * 1024 + koff); if (ks & 1) kfa[kk] = t; else kfb[kk] = t; }
;                 }
;                 __builtin_amdgcn_sched_barrier(0);
;                 s[ks][0] = (f32x4){0.f, 0.f, 0.f, 0.f}; s[ks][1] = (f32x4){0.f, 0.f, 0.f, 0.f};
; #pragma unroll
;                 for (int kk = 0; kk < KK; ++kk) { const bf16x8 kf = (ks & 1) ? kfb[kk] : kfa[kk];
;                     const bf16x8 qa0 = qf[0][kk], qa1 = qf[1][kk];
;                     s[ks][0] = __builtin_amdgcn_mfma_f32_16x16x32_bf16(kf, qa0, s[ks][0], 0, 0, 0);
;                     s[ks][1] = __builtin_amdgcn_mfma_f32_16x16x32_bf16(kf, qa1, s[ks][1], 0, 0, 0); }
;                 __builtin_amdgcn_sched_barrier(0);
;             }
;         }
;         if (ST) { asm volatile("" ::: "memory"); __builtin_amdgcn_s_barrier(); asm volatile("" ::: "memory"); }
;         if (act) {
;             if (MB) {
;                 const unsigned long long mw0 = sm0[kt], mw1 = sm1[kt];
;                 if (pass == 0) {
; #pragma unroll
;                     for (int ks = 0; ks < 4; ++ks) { const unsigned b0 = (unsigned)(mw0 >> (16 * ks + 4 * q)) & 0xFu, b1 = (unsigned)(mw1 >> (16 * ks + 4 * q)) & 0xFu;
; #pragma unroll
;                         for (int j = 0; j < 4; ++j) { s[ks][0][j] = ((b0 >> j) & 1u) ? s[ks][0][j] + tbfar : -INFINITY; s[ks][1][j] = ((b1 >> j) & 1u) ? s[ks][1][j] + tbfar : -INFINITY; } }
.LBB0_665:
	v_lshl_add_u32 v156, s45, 14, v181
	ds_read_b128 v[124:127], v156
	ds_read_b128 v[128:131], v156 offset:1024
	ds_read_b128 v[132:135], v156 offset:2048
	ds_read_b128 v[136:139], v156 offset:3072
	ds_read_b128 v[140:143], v156 offset:4096
	ds_read_b128 v[160:163], v156 offset:5120
	ds_read_b128 v[164:167], v156 offset:6144
	ds_read_b128 v[186:189], v156 offset:7168
	s_waitcnt lgkmcnt(7)
	v_mfma_f32_16x16x32_bf16 v[190:193], v[124:127], v[44:47], 0
	v_mfma_f32_16x16x32_bf16 v[124:127], v[124:127], v[60:63], 0
	s_waitcnt lgkmcnt(6)
	v_mfma_f32_16x16x32_bf16 v[190:193], v[128:131], v[64:67], v[190:193]
	v_mfma_f32_16x16x32_bf16 v[124:127], v[128:131], v[72:75], v[124:127]
	s_waitcnt lgkmcnt(5)
	v_mfma_f32_16x16x32_bf16 v[128:131], v[132:135], v[68:71], v[190:193]
	v_mfma_f32_16x16x32_bf16 v[124:127], v[132:135], v[76:79], v[124:127]
	s_waitcnt lgkmcnt(4)
	v_mfma_f32_16x16x32_bf16 v[128:131], v[136:139], v[80:83], v[128:131]
	v_mfma_f32_16x16x32_bf16 v[124:127], v[136:139], v[56:59], v[124:127]
	ds_read_b128 v[132:135], v156 offset:8192
	ds_read_b128 v[136:139], v156 offset:9216
	ds_read_b128 v[190:193], v156 offset:10240
	ds_read_b128 v[194:197], v156 offset:11264
	s_waitcnt lgkmcnt(7)
	v_mfma_f32_16x16x32_bf16 v[198:201], v[140:143], v[44:47], 0
	v_mfma_f32_16x16x32_bf16 v[140:143], v[140:143], v[60:63], 0
	s_waitcnt lgkmcnt(6)
	v_mfma_f32_16x16x32_bf16 v[198:201], v[160:163], v[64:67], v[198:201]
	v_mfma_f32_16x16x32_bf16 v[140:143], v[160:163], v[72:75], v[140:143]
	s_waitcnt lgkmcnt(5)
	v_mfma_f32_16x16x32_bf16 v[160:163], v[164:167], v[68:71], v[198:201]
	v_mfma_f32_16x16x32_bf16 v[140:143], v[164:167], v[76:79], v[140:143]
	s_waitcnt lgkmcnt(4)
	v_mfma_f32_16x16x32_bf16 v[160:163], v[186:189], v[80:83], v[160:163]
	v_mfma_f32_16x16x32_bf16 v[140:143], v[186:189], v[56:59], v[140:143]
	ds_read_b128 v[164:167], v156 offset:12288
	ds_read_b128 v[186:189], v156 offset:13312
	ds_read_b128 v[198:201], v156 offset:14336
	ds_read_b128 v[202:205], v156 offset:15360
	s_waitcnt lgkmcnt(7)
	v_mfma_f32_16x16x32_bf16 v[206:209], v[132:135], v[44:47], 0
	v_mfma_f32_16x16x32_bf16 v[132:135], v[132:135], v[60:63], 0
	s_waitcnt lgkmcnt(6)
	v_mfma_f32_16x16x32_bf16 v[206:209], v[136:139], v[64:67], v[206:209]
	v_mfma_f32_16x16x32_bf16 v[132:135], v[136:139], v[72:75], v[132:135]
	s_waitcnt lgkmcnt(5)
	v_mfma_f32_16x16x32_bf16 v[136:139], v[190:193], v[68:71], v[206:209]
	v_mfma_f32_16x16x32_bf16 v[132:135], v[190:193], v[76:79], v[132:135]
	s_waitcnt lgkmcnt(4)
	v_mfma_f32_16x16x32_bf16 v[136:139], v[194:197], v[80:83], v[136:139]
	v_mfma_f32_16x16x32_bf16 v[132:135], v[194:197], v[56:59], v[132:135]
	s_waitcnt lgkmcnt(3)
	v_mfma_f32_16x16x32_bf16 v[190:193], v[164:167], v[44:47], 0
	v_mfma_f32_16x16x32_bf16 v[164:167], v[164:167], v[60:63], 0
	s_waitcnt lgkmcnt(2)
	v_mfma_f32_16x16x32_bf16 v[164:167], v[186:189], v[72:75], v[164:167]
	v_mfma_f32_16x16x32_bf16 v[190:193], v[186:189], v[64:67], v[190:193]
	s_waitcnt lgkmcnt(1)
	v_mfma_f32_16x16x32_bf16 v[164:167], v[198:201], v[76:79], v[164:167]
	v_mfma_f32_16x16x32_bf16 v[186:189], v[198:201], v[68:71], v[190:193]
	s_waitcnt lgkmcnt(0)
	v_mfma_f32_16x16x32_bf16 v[164:167], v[202:205], v[56:59], v[164:167]
	v_mfma_f32_16x16x32_bf16 v[186:189], v[202:205], v[80:83], v[186:189]
	v_mov_b32_e32 v156, s4
	s_nop 0
	ds_read2_b64 v[190:193], v156 offset1:32
	s_nop 3
	v_mov_b32_e32 v158, v164
	s_waitcnt lgkmcnt(0)
	v_lshrrev_b64 v[156:157], v150, v[192:193]
	v_bfe_i32 v243, v156, 0, 1
	v_bfe_i32 v244, v156, 1, 1
	v_bfi_b32 v168, v243, v158, v155
	v_bfe_i32 v245, v156, 2, 1
	v_bfi_b32 v169, v244, v165, v155
	v_bfe_i32 v246, v156, 3, 1
	v_bfi_b32 v166, v245, v166, v155
	s_mul_i32 s47, s45, 0x4400
	v_bfi_b32 v185, v246, v167, v155
	v_lshrrev_b64 v[156:157], v150, v[190:191]
	v_bfe_i32 v247, v156, 0, 1
	v_bfe_i32 v243, v156, 1, 1
	v_bfe_i32 v244, v156, 2, 1
	v_bfi_b32 v158, v247, v186, v155
	v_bfe_i32 v245, v156, 3, 1
	v_bfi_b32 v164, v243, v187, v155
	v_bfi_b32 v167, v244, v188, v155
	v_bfi_b32 v183, v245, v189, v155
	v_lshrrev_b64 v[156:157], v152, v[192:193]
	v_bfe_i32 v246, v156, 0, 1
	v_bfi_b32 v186, v246, v132, v155
	v_bfe_i32 v247, v156, 1, 1
	v_bfe_i32 v243, v156, 2, 1
	v_bfi_b32 v187, v247, v133, v155
	v_bfe_i32 v244, v156, 3, 1
	v_bfi_b32 v188, v243, v134, v155
	v_bfi_b32 v189, v244, v135, v155
	v_lshrrev_b64 v[132:133], v152, v[190:191]
	v_bfe_i32 v245, v132, 0, 1
	v_bfe_i32 v246, v132, 1, 1
	v_bfi_b32 v134, v245, v136, v155
	v_bfe_i32 v247, v132, 2, 1
	v_bfe_i32 v243, v132, 3, 1
	v_bfi_b32 v136, v246, v137, v155
	v_lshrrev_b32_e32 v135, v154, v192
	v_bfe_i32 v244, v135, 0, 1
	v_bfi_b32 v138, v247, v138, v155
	v_bfi_b32 v156, v243, v139, v155
	v_lshrrev_b64 v[132:133], v154, v[192:193]
	v_bfe_i32 v245, v132, 1, 1
	v_bfi_b32 v194, v244, v140, v155
	v_bfe_i32 v246, v132, 2, 1
	v_bfe_i32 v247, v132, 3, 1
	v_bfi_b32 v195, v245, v141, v155
	v_lshrrev_b32_e32 v135, v154, v190
	v_bfe_i32 v243, v135, 0, 1
	v_bfi_b32 v196, v246, v142, v155
	v_bfi_b32 v197, v247, v143, v155
	v_lshrrev_b64 v[132:133], v154, v[190:191]
	v_bfe_i32 v244, v132, 1, 1
	v_bfi_b32 v135, v243, v160, v155
	v_bfe_i32 v245, v132, 2, 1
	v_bfe_i32 v246, v132, 3, 1
	v_bfi_b32 v140, v244, v161, v155
	v_bfi_b32 v142, v245, v162, v155
	v_bfi_b32 v160, v246, v163, v155
	v_lshrrev_b64 v[132:133], v179, v[192:193]
	v_lshrrev_b32_e32 v133, v179, v192
	v_bfe_i32 v247, v133, 0, 1
	v_bfe_i32 v243, v132, 2, 1
	v_bfi_b32 v162, v247, v124, v155
	v_bfe_i32 v244, v132, 1, 1
	v_bfe_i32 v245, v132, 3, 1
	v_bfi_b32 v192, v244, v125, v155
	v_lshrrev_b64 v[124:125], v179, v[190:191]
	v_mov_b32_e32 v125, v128
	v_lshrrev_b32_e32 v128, v179, v190
	v_bfe_i32 v246, v128, 0, 1
	v_mov_b32_e32 v128, v129
	v_bfe_i32 v247, v124, 1, 1
	v_bfi_b32 v125, v246, v125, v155
	v_mov_b32_e32 v129, v130
	v_bfe_i32 v244, v124, 2, 1
	v_bfi_b32 v128, v247, v128, v155
	v_bfe_i32 v246, v124, 3, 1
	v_bfi_b32 v129, v244, v129, v155
	v_bfi_b32 v124, v246, v131, v155
	v_max3_f32 v130, v125, s79, v128
	v_max3_f32 v130, v130, v129, v124
	v_max3_f32 v130, v130, v135, v140
	v_max3_f32 v130, v130, v142, v160
	v_max3_f32 v130, v130, v134, v136
	v_max3_f32 v130, v130, v138, v156
	v_max3_f32 v130, v130, v158, v164
	v_max3_f32 v130, v130, v167, v183
	ds_bpermute_b32 v131, v159, v130
	s_waitcnt lgkmcnt(0)
; template <int DQK, bool MB> ...
;     ...
;             for (int ct = 0; ct < 2; ++ct) {
;                 float mx = -INFINITY;
; #pragma unroll
;                 for (int ks = 0; ks < 4; ++ks)
; #pragma unroll
;                     for (int j = 0; j < 4; ++j) mx = fmaxf(mx, s[ks][ct][j]);
;                 mx = fmaxf(mx, __shfl_xor(mx, 16)); mx = fmaxf(mx, __shfl_xor(mx, 32));
;                 const float mnew = fmaxf(mrow[ct], mx), alpha = __builtin_amdgcn_exp2f(mrow[ct] - mnew);
;                 mrow[ct] = mnew;
;                 float ps = 0.f;
; #pragma unroll
;                 for (int ks = 0; ks < 4; ++ks)
; #pragma unroll
;                     for (int j = 0; j < 4; ++j) { const float p = __builtin_amdgcn_exp2f(s[ks][ct][j] - mnew); s[ks][ct][j] = p; ps += p; }
;                 lsum[ct] = lsum[ct] * alpha + ps; alpha2[ct] = alpha;
;             }
;             {
; #pragma unroll
;                 for (int ct = 0; ct < 2; ++ct)
; #pragma unroll
;                     for (int dt = 0; dt < 8; ++dt) o[ct][dt] *= alpha2[ct];
	v_max_f32_e32 v131, v131, v131
	v_max_f32_e32 v130, v130, v131
	ds_bpermute_b32 v131, v184, v130
	v_bfi_b32 v126, v243, v126, v155
	s_waitcnt lgkmcnt(0)
	v_max_f32_e32 v182, v130, v131
	v_add_f32_e32 v182, v113, v182
	v_max_f32_e32 v182, v123, v182
	v_sub_f32_e32 v241, v182, v123
	v_cmp_lt_f32_e64 s[98:99], 4.0, v241
	s_nop 1
	v_cndmask_b32_e64 v182, v123, v182, s[98:99]
	v_sub_f32_e32 v241, v182, v113
	v_sub_f32_e32 v130, v123, v182
	v_sub_f32_e32 v123, v125, v241
	v_bfi_b32 v132, v245, v127, v155
	v_exp_f32_e32 v157, v123
	v_sub_f32_e32 v123, v128, v241
	v_max3_f32 v128, v162, s79, v192
	v_max3_f32 v128, v128, v126, v132
	v_exp_f32_e32 v143, v123
	v_sub_f32_e32 v123, v129, v241
	v_max3_f32 v128, v128, v194, v195
	v_exp_f32_e32 v141, v123
	v_sub_f32_e32 v123, v124, v241
	v_max3_f32 v128, v128, v196, v197
	v_exp_f32_e32 v139, v123
	v_sub_f32_e32 v123, v135, v241
	v_max3_f32 v128, v128, v186, v187
	v_exp_f32_e32 v137, v123
	v_sub_f32_e32 v123, v140, v241
	v_max3_f32 v128, v128, v188, v189
	v_exp_f32_e32 v135, v123
	v_sub_f32_e32 v123, v142, v241
	v_max3_f32 v128, v128, v168, v169
	v_exp_f32_e32 v133, v123
	v_sub_f32_e32 v123, v160, v241
	v_max3_f32 v128, v128, v166, v185
	v_exp_f32_e32 v131, v123
	v_sub_f32_e32 v123, v134, v241
	ds_bpermute_b32 v134, v159, v128
	v_sub_f32_e32 v124, v158, v241
	v_exp_f32_e32 v165, v124
	v_sub_f32_e32 v124, v164, v241
	v_exp_f32_e32 v161, v124
	s_waitcnt lgkmcnt(0)
	v_max_f32_e32 v134, v134, v134
	v_max_f32_e32 v128, v128, v134
	ds_bpermute_b32 v134, v184, v128
	v_sub_f32_e32 v124, v167, v241
	v_exp_f32_e32 v129, v123
	v_sub_f32_e32 v123, v136, v241
	v_exp_f32_e32 v167, v124
	v_sub_f32_e32 v124, v183, v241
	s_waitcnt lgkmcnt(0)
	v_max_f32_e32 v183, v128, v134
	v_add_f32_e32 v183, v113, v183
	v_max_f32_e32 v183, v122, v183
	v_sub_f32_e32 v242, v183, v122
	v_cmp_lt_f32_e64 s[100:101], 4.0, v242
	s_nop 1
	v_cndmask_b32_e64 v183, v122, v183, s[100:101]
	v_sub_f32_e32 v242, v183, v113
	v_exp_f32_e32 v127, v123
	v_sub_f32_e32 v123, v138, v241
	v_sub_f32_e32 v190, v122, v183
	v_sub_f32_e32 v122, v162, v242
	v_exp_f32_e32 v125, v123
	v_sub_f32_e32 v123, v156, v241
	v_exp_f32_e32 v156, v122
	v_sub_f32_e32 v122, v192, v242
	v_exp_f32_e32 v142, v122
	v_sub_f32_e32 v122, v126, v242
	v_exp_f32_e32 v140, v122
	v_sub_f32_e32 v122, v132, v242
	v_exp_f32_e32 v138, v122
	v_sub_f32_e32 v122, v194, v242
	v_exp_f32_e32 v136, v122
	v_sub_f32_e32 v122, v195, v242
	v_exp_f32_e32 v134, v122
	v_sub_f32_e32 v122, v196, v242
	v_sub_f32_e32 v160, v168, v242
	v_exp_f32_e32 v168, v190
	v_exp_f32_e32 v132, v122
	v_sub_f32_e32 v122, v197, v242
	v_exp_f32_e32 v158, v130
	v_exp_f32_e32 v130, v122
	v_sub_f32_e32 v122, v186, v242
	v_exp_f32_e32 v128, v122
	v_sub_f32_e32 v122, v187, v242
	v_exp_f32_e32 v126, v122
	v_sub_f32_e32 v122, v188, v242
	v_exp_f32_e32 v164, v160
	v_sub_f32_e32 v160, v169, v242
	v_sub_f32_e32 v162, v166, v242
	v_add_u32_e32 v169, s47, v180
	v_exp_f32_e32 v163, v124
	v_exp_f32_e32 v124, v122
	v_sub_f32_e32 v122, v189, v242
	v_exp_f32_e32 v166, v162
	v_sub_f32_e32 v162, v185, v242
	v_add_u32_e32 v185, 0x8000, v169
	v_add_u32_e32 v222, 0x8800, v169
	v_add_u32_e32 v223, 0x9000, v169
	v_add_u32_e32 v225, 0x9800, v169
	v_add_u32_e32 v230, 0xa000, v169
	v_add_u32_e32 v231, 0xa800, v169
	v_add_u32_e32 v232, 0xb000, v169
	v_add_u32_e32 v169, 0xb800, v169
	v_exp_f32_e32 v123, v123
	v_exp_f32_e32 v122, v122
	v_exp_f32_e32 v160, v160
	v_exp_f32_e32 v162, v162
	s_or_b64 s[98:99], s[98:99], s[100:101]
	s_cmp_eq_u64 s[98:99], 0
	s_cbranch_scc1 .Llazy_bf_skip
	v_pk_mul_f32 v[30:31], v[30:31], v[168:169] op_sel_hi:[1,0]
	v_pk_mul_f32 v[28:29], v[28:29], v[168:169] op_sel_hi:[1,0]
	v_pk_mul_f32 v[26:27], v[26:27], v[168:169] op_sel_hi:[1,0]
	v_pk_mul_f32 v[24:25], v[24:25], v[168:169] op_sel_hi:[1,0]
	v_pk_mul_f32 v[22:23], v[22:23], v[168:169] op_sel_hi:[1,0]
	v_pk_mul_f32 v[20:21], v[20:21], v[168:169] op_sel_hi:[1,0]
	v_pk_mul_f32 v[18:19], v[18:19], v[168:169] op_sel_hi:[1,0]
	v_pk_mul_f32 v[16:17], v[16:17], v[168:169] op_sel_hi:[1,0]
	v_pk_mul_f32 v[14:15], v[14:15], v[168:169] op_sel_hi:[1,0]
	v_pk_mul_f32 v[12:13], v[12:13], v[168:169] op_sel_hi:[1,0]
	v_pk_mul_f32 v[10:11], v[10:11], v[168:169] op_sel_hi:[1,0]
	v_pk_mul_f32 v[8:9], v[8:9], v[168:169] op_sel_hi:[1,0]
	v_pk_mul_f32 v[6:7], v[6:7], v[168:169] op_sel_hi:[1,0]
	v_pk_mul_f32 v[4:5], v[4:5], v[168:169] op_sel_hi:[1,0]
	v_pk_mul_f32 v[2:3], v[2:3], v[168:169] op_sel_hi:[1,0]
	v_pk_mul_f32 v[0:1], v[0:1], v[168:169] op_sel_hi:[1,0]
	v_pk_mul_f32 v[110:111], v[110:111], v[158:159] op_sel_hi:[1,0]
	v_pk_mul_f32 v[108:109], v[108:109], v[158:159] op_sel_hi:[1,0]
	v_pk_mul_f32 v[106:107], v[106:107], v[158:159] op_sel_hi:[1,0]
	v_pk_mul_f32 v[104:105], v[104:105], v[158:159] op_sel_hi:[1,0]
	v_pk_mul_f32 v[102:103], v[102:103], v[158:159] op_sel_hi:[1,0]
	v_pk_mul_f32 v[100:101], v[100:101], v[158:159] op_sel_hi:[1,0]
	v_pk_mul_f32 v[98:99], v[98:99], v[158:159] op_sel_hi:[1,0]
	v_pk_mul_f32 v[96:97], v[96:97], v[158:159] op_sel_hi:[1,0]
	v_pk_mul_f32 v[86:87], v[86:87], v[158:159] op_sel_hi:[1,0]
	v_pk_mul_f32 v[84:85], v[84:85], v[158:159] op_sel_hi:[1,0]
	v_pk_mul_f32 v[42:43], v[42:43], v[158:159] op_sel_hi:[1,0]
	v_pk_mul_f32 v[40:41], v[40:41], v[158:159] op_sel_hi:[1,0]
	v_pk_mul_f32 v[38:39], v[38:39], v[158:159] op_sel_hi:[1,0]
	v_pk_mul_f32 v[36:37], v[36:37], v[158:159] op_sel_hi:[1,0]
	v_pk_mul_f32 v[34:35], v[34:35], v[158:159] op_sel_hi:[1,0]
	v_pk_mul_f32 v[32:33], v[32:33], v[158:159] op_sel_hi:[1,0]
